# odin epilogue fast path extended to sample-row tiles: RoPE applied in registers (table loads batched per block, ds_bpermute partner), then the same LDS-staged dwordx4 stores; V segment still compiled
# speedup vs baseline: 1.0064x; 1.0058x over previous
.LBB0_1518:
	s_lshr_b32 s12, s10, 10
	s_cmp_ge_u32 s12, 2
	s_cbranch_scc1 .Lodin4_old
	v_lshl_or_b32 v116, v183, 3, v191
	v_lshrrev_b32_e32 v117, 6, v116
	v_and_b32_e32 v118, 63, v116
	v_lshlrev_b32_e32 v113, 11, v117
	v_add_u32_e32 v113, 0x10000, v113
	v_readfirstlane_b32 s6, v117
	v_and_b32_e32 v116, 31, v118
	v_lshl_add_u32 v112, v116, 1, v113
	v_lshrrev_b32_e32 v117, 5, v118
	v_lshl_add_u32 v112, v117, 8, v112
	v_lshl_add_u32 v113, v118, 4, v113
	v_lshlrev_b32_e32 v115, 2, v116
	v_lshl_add_u32 v115, v117, 14, v115
	v_lshrrev_b32_e32 v117, 2, v118
	v_and_b32_e32 v114, 3, v118
	v_lshlrev_b32_e32 v114, 4, v114
	v_lshl_add_u32 v114, v117, 11, v114
	s_lshr_b32 s7, s6, 1
	s_lshl_b32 s7, s7, 6
	s_add_u32 s7, s7, s11
	s_and_b32 s6, s6, 1
	s_lshl_b32 s6, s6, 6
	s_and_b32 s8, s10, 0x3ff
	s_add_u32 s6, s6, s8
	s_cmp_ge_u32 s11, 0x2000
	s_cbranch_scc1 .Lodin4_rope
.Lodin4_norope:
	s_cmp_lg_u32 s12, 0
	s_cbranch_scc1 .Lodin4_kseg
	v_mul_f32_e32 v48, 0x3e38aa3b, v48
	v_mul_f32_e32 v49, 0x3e38aa3b, v49
	v_mul_f32_e32 v50, 0x3e38aa3b, v50
	v_mul_f32_e32 v51, 0x3e38aa3b, v51
	v_mul_f32_e32 v52, 0x3e38aa3b, v52
	v_mul_f32_e32 v53, 0x3e38aa3b, v53
	v_mul_f32_e32 v54, 0x3e38aa3b, v54
	v_mul_f32_e32 v55, 0x3e38aa3b, v55
	v_mul_f32_e32 v56, 0x3e38aa3b, v56
	v_mul_f32_e32 v57, 0x3e38aa3b, v57
	v_mul_f32_e32 v58, 0x3e38aa3b, v58
	v_mul_f32_e32 v59, 0x3e38aa3b, v59
	v_mul_f32_e32 v60, 0x3e38aa3b, v60
	v_mul_f32_e32 v61, 0x3e38aa3b, v61
	v_mul_f32_e32 v62, 0x3e38aa3b, v62
	v_mul_f32_e32 v63, 0x3e38aa3b, v63
	v_mul_f32_e32 v16, 0x3e38aa3b, v16
	v_mul_f32_e32 v17, 0x3e38aa3b, v17
	v_mul_f32_e32 v18, 0x3e38aa3b, v18
	v_mul_f32_e32 v19, 0x3e38aa3b, v19
	v_mul_f32_e32 v20, 0x3e38aa3b, v20
	v_mul_f32_e32 v21, 0x3e38aa3b, v21
	v_mul_f32_e32 v22, 0x3e38aa3b, v22
	v_mul_f32_e32 v23, 0x3e38aa3b, v23
	v_mul_f32_e32 v24, 0x3e38aa3b, v24
	v_mul_f32_e32 v25, 0x3e38aa3b, v25
	v_mul_f32_e32 v26, 0x3e38aa3b, v26
	v_mul_f32_e32 v27, 0x3e38aa3b, v27
	v_mul_f32_e32 v28, 0x3e38aa3b, v28
	v_mul_f32_e32 v29, 0x3e38aa3b, v29
	v_mul_f32_e32 v30, 0x3e38aa3b, v30
	v_mul_f32_e32 v31, 0x3e38aa3b, v31
	v_mul_f32_e32 v32, 0x3e38aa3b, v32
	v_mul_f32_e32 v33, 0x3e38aa3b, v33
	v_mul_f32_e32 v34, 0x3e38aa3b, v34
	v_mul_f32_e32 v35, 0x3e38aa3b, v35
	v_mul_f32_e32 v36, 0x3e38aa3b, v36
	v_mul_f32_e32 v37, 0x3e38aa3b, v37
	v_mul_f32_e32 v38, 0x3e38aa3b, v38
	v_mul_f32_e32 v39, 0x3e38aa3b, v39
	v_mul_f32_e32 v40, 0x3e38aa3b, v40
	v_mul_f32_e32 v41, 0x3e38aa3b, v41
	v_mul_f32_e32 v42, 0x3e38aa3b, v42
	v_mul_f32_e32 v43, 0x3e38aa3b, v43
	v_mul_f32_e32 v44, 0x3e38aa3b, v44
	v_mul_f32_e32 v45, 0x3e38aa3b, v45
	v_mul_f32_e32 v46, 0x3e38aa3b, v46
	v_mul_f32_e32 v47, 0x3e38aa3b, v47
	v_mul_f32_e32 v0, 0x3e38aa3b, v0
	v_mul_f32_e32 v1, 0x3e38aa3b, v1
	v_mul_f32_e32 v2, 0x3e38aa3b, v2
	v_mul_f32_e32 v3, 0x3e38aa3b, v3
	v_mul_f32_e32 v4, 0x3e38aa3b, v4
	v_mul_f32_e32 v5, 0x3e38aa3b, v5
	v_mul_f32_e32 v6, 0x3e38aa3b, v6
	v_mul_f32_e32 v7, 0x3e38aa3b, v7
	v_mul_f32_e32 v8, 0x3e38aa3b, v8
	v_mul_f32_e32 v9, 0x3e38aa3b, v9
	v_mul_f32_e32 v10, 0x3e38aa3b, v10
	v_mul_f32_e32 v11, 0x3e38aa3b, v11
	v_mul_f32_e32 v12, 0x3e38aa3b, v12
	v_mul_f32_e32 v13, 0x3e38aa3b, v13
	v_mul_f32_e32 v14, 0x3e38aa3b, v14
	v_mul_f32_e32 v15, 0x3e38aa3b, v15
	s_mov_b32 s9, 0x3971900
	s_branch .Lodin4_nat
.Lodin4_kseg:
	s_cmp_ge_u32 s11, 0x2000
	s_cbranch_scc1 .Lodin4_kbase
	s_lshl_b32 s8, s7, 12
	s_lshl_b32 s9, s6, 2
	s_add_u32 s8, s8, s9
	s_add_u32 s8, s8, 0x3000000
	s_add_u32 s98, s88, s8
	s_addc_u32 s99, s89, 0
	global_store_dword v115, v48, s[98:99]
	global_store_dword v115, v16, s[98:99] offset:128
	s_add_u32 s98, s98, 0x1000
	s_addc_u32 s99, s99, 0
	global_store_dword v115, v49, s[98:99]
	global_store_dword v115, v17, s[98:99] offset:128
	s_add_u32 s98, s98, 0x1000
	s_addc_u32 s99, s99, 0
	global_store_dword v115, v50, s[98:99]
	global_store_dword v115, v18, s[98:99] offset:128
	s_add_u32 s98, s98, 0x1000
	s_addc_u32 s99, s99, 0
	global_store_dword v115, v51, s[98:99]
	global_store_dword v115, v19, s[98:99] offset:128
	s_add_u32 s98, s98, 0x5000
	s_addc_u32 s99, s99, 0
	global_store_dword v115, v52, s[98:99]
	global_store_dword v115, v20, s[98:99] offset:128
	s_add_u32 s98, s98, 0x1000
	s_addc_u32 s99, s99, 0
	global_store_dword v115, v53, s[98:99]
	global_store_dword v115, v21, s[98:99] offset:128
	s_add_u32 s98, s98, 0x1000
	s_addc_u32 s99, s99, 0
	global_store_dword v115, v54, s[98:99]
	global_store_dword v115, v22, s[98:99] offset:128
	s_add_u32 s98, s98, 0x1000
	s_addc_u32 s99, s99, 0
	global_store_dword v115, v55, s[98:99]
	global_store_dword v115, v23, s[98:99] offset:128
	s_add_u32 s98, s98, 0x5000
	s_addc_u32 s99, s99, 0
	global_store_dword v115, v56, s[98:99]
	global_store_dword v115, v24, s[98:99] offset:128
	s_add_u32 s98, s98, 0x1000
	s_addc_u32 s99, s99, 0
	global_store_dword v115, v57, s[98:99]
	global_store_dword v115, v25, s[98:99] offset:128
	s_add_u32 s98, s98, 0x1000
	s_addc_u32 s99, s99, 0
	global_store_dword v115, v58, s[98:99]
	global_store_dword v115, v26, s[98:99] offset:128
	s_add_u32 s98, s98, 0x1000
	s_addc_u32 s99, s99, 0
	global_store_dword v115, v59, s[98:99]
	global_store_dword v115, v27, s[98:99] offset:128
	s_add_u32 s98, s98, 0x5000
	s_addc_u32 s99, s99, 0
	global_store_dword v115, v60, s[98:99]
	global_store_dword v115, v28, s[98:99] offset:128
	s_add_u32 s98, s98, 0x1000
	s_addc_u32 s99, s99, 0
	global_store_dword v115, v61, s[98:99]
	global_store_dword v115, v29, s[98:99] offset:128
	s_add_u32 s98, s98, 0x1000
	s_addc_u32 s99, s99, 0
	global_store_dword v115, v62, s[98:99]
	global_store_dword v115, v30, s[98:99] offset:128
	s_add_u32 s98, s98, 0x1000
	s_addc_u32 s99, s99, 0
	global_store_dword v115, v63, s[98:99]
	global_store_dword v115, v31, s[98:99] offset:128
	s_add_u32 s98, s98, 0x5000
	s_addc_u32 s99, s99, 0
	global_store_dword v115, v32, s[98:99]
	global_store_dword v115, v0, s[98:99] offset:128
	s_add_u32 s98, s98, 0x1000
	s_addc_u32 s99, s99, 0
	global_store_dword v115, v33, s[98:99]
	global_store_dword v115, v1, s[98:99] offset:128
	s_add_u32 s98, s98, 0x1000
	s_addc_u32 s99, s99, 0
	global_store_dword v115, v34, s[98:99]
	global_store_dword v115, v2, s[98:99] offset:128
	s_add_u32 s98, s98, 0x1000
	s_addc_u32 s99, s99, 0
	global_store_dword v115, v35, s[98:99]
	global_store_dword v115, v3, s[98:99] offset:128
	s_add_u32 s98, s98, 0x5000
	s_addc_u32 s99, s99, 0
	global_store_dword v115, v36, s[98:99]
	global_store_dword v115, v4, s[98:99] offset:128
	s_add_u32 s98, s98, 0x1000
	s_addc_u32 s99, s99, 0
	global_store_dword v115, v37, s[98:99]
	global_store_dword v115, v5, s[98:99] offset:128
	s_add_u32 s98, s98, 0x1000
	s_addc_u32 s99, s99, 0
	global_store_dword v115, v38, s[98:99]
	global_store_dword v115, v6, s[98:99] offset:128
	s_add_u32 s98, s98, 0x1000
	s_addc_u32 s99, s99, 0
	global_store_dword v115, v39, s[98:99]
	global_store_dword v115, v7, s[98:99] offset:128
	s_add_u32 s98, s98, 0x5000
	s_addc_u32 s99, s99, 0
	global_store_dword v115, v40, s[98:99]
	global_store_dword v115, v8, s[98:99] offset:128
	s_add_u32 s98, s98, 0x1000
	s_addc_u32 s99, s99, 0
	global_store_dword v115, v41, s[98:99]
	global_store_dword v115, v9, s[98:99] offset:128
	s_add_u32 s98, s98, 0x1000
	s_addc_u32 s99, s99, 0
	global_store_dword v115, v42, s[98:99]
	global_store_dword v115, v10, s[98:99] offset:128
	s_add_u32 s98, s98, 0x1000
	s_addc_u32 s99, s99, 0
	global_store_dword v115, v43, s[98:99]
	global_store_dword v115, v11, s[98:99] offset:128
	s_add_u32 s98, s98, 0x5000
	s_addc_u32 s99, s99, 0
	global_store_dword v115, v44, s[98:99]
	global_store_dword v115, v12, s[98:99] offset:128
	s_add_u32 s98, s98, 0x1000
	s_addc_u32 s99, s99, 0
	global_store_dword v115, v45, s[98:99]
	global_store_dword v115, v13, s[98:99] offset:128
	s_add_u32 s98, s98, 0x1000
	s_addc_u32 s99, s99, 0
	global_store_dword v115, v46, s[98:99]
	global_store_dword v115, v14, s[98:99] offset:128
	s_add_u32 s98, s98, 0x1000
	s_addc_u32 s99, s99, 0
	global_store_dword v115, v47, s[98:99]
	global_store_dword v115, v15, s[98:99] offset:128
.Lodin4_kbase:
	s_mov_b32 s9, 0x5171900

.Lodin4_rope:
	v_xor_b32_e32 v119, 16, v118
	v_lshlrev_b32_e32 v119, 2, v119
	v_and_b32_e32 v116, 16, v118
	v_cmp_eq_u32_e64 s[100:101], 0, v116
	v_and_b32_e32 v116, 15, v118
	v_lshlrev_b32_e32 v116, 3, v116
	v_lshrrev_b32_e32 v117, 5, v118
	v_lshl_add_u32 v117, v117, 9, v116
	s_sub_u32 s8, s7, 0x2000
	s_bfe_u32 s8, s8, 0x50006
	s_lshl_b32 s8, s8, 7
	s_add_u32 s8, s8, 0x3464000
	s_add_u32 s98, s90, s8
	s_addc_u32 s99, s91, 0
	global_load_dwordx2 v[120:121], v116, s[98:99]
	ds_bpermute_b32 v64, v119, v48
	ds_bpermute_b32 v65, v119, v49
	ds_bpermute_b32 v66, v119, v50
	ds_bpermute_b32 v67, v119, v51
	ds_bpermute_b32 v68, v119, v52
	ds_bpermute_b32 v69, v119, v53
	ds_bpermute_b32 v70, v119, v54
	ds_bpermute_b32 v71, v119, v55
	ds_bpermute_b32 v72, v119, v56
	ds_bpermute_b32 v73, v119, v57
	ds_bpermute_b32 v74, v119, v58
	ds_bpermute_b32 v75, v119, v59
	ds_bpermute_b32 v76, v119, v60
	ds_bpermute_b32 v77, v119, v61
	ds_bpermute_b32 v78, v119, v62
	ds_bpermute_b32 v79, v119, v63
	s_waitcnt vmcnt(0) lgkmcnt(0)
	v_mul_f32_e32 v64, v121, v64
	v_mul_f32_e32 v65, v121, v65
	v_mul_f32_e32 v66, v121, v66
	v_mul_f32_e32 v67, v121, v67
	v_mul_f32_e32 v68, v121, v68
	v_mul_f32_e32 v69, v121, v69
	v_mul_f32_e32 v70, v121, v70
	v_mul_f32_e32 v71, v121, v71
	v_mul_f32_e32 v72, v121, v72
	v_mul_f32_e32 v73, v121, v73
	v_mul_f32_e32 v74, v121, v74
	v_mul_f32_e32 v75, v121, v75
	v_mul_f32_e32 v76, v121, v76
	v_mul_f32_e32 v77, v121, v77
	v_mul_f32_e32 v78, v121, v78
	v_mul_f32_e32 v79, v121, v79
	v_cndmask_b32_e64 v64, v64, -v64, s[100:101]
	v_cndmask_b32_e64 v65, v65, -v65, s[100:101]
	v_cndmask_b32_e64 v66, v66, -v66, s[100:101]
	v_cndmask_b32_e64 v67, v67, -v67, s[100:101]
	v_cndmask_b32_e64 v68, v68, -v68, s[100:101]
	v_cndmask_b32_e64 v69, v69, -v69, s[100:101]
	v_cndmask_b32_e64 v70, v70, -v70, s[100:101]
	v_cndmask_b32_e64 v71, v71, -v71, s[100:101]
	v_cndmask_b32_e64 v72, v72, -v72, s[100:101]
	v_cndmask_b32_e64 v73, v73, -v73, s[100:101]
	v_cndmask_b32_e64 v74, v74, -v74, s[100:101]
	v_cndmask_b32_e64 v75, v75, -v75, s[100:101]
	v_cndmask_b32_e64 v76, v76, -v76, s[100:101]
	v_cndmask_b32_e64 v77, v77, -v77, s[100:101]
	v_cndmask_b32_e64 v78, v78, -v78, s[100:101]
	v_cndmask_b32_e64 v79, v79, -v79, s[100:101]
	v_fma_f32 v48, v48, v120, v64
	v_fma_f32 v49, v49, v120, v65
	v_fma_f32 v50, v50, v120, v66
	v_fma_f32 v51, v51, v120, v67
	v_fma_f32 v52, v52, v120, v68
	v_fma_f32 v53, v53, v120, v69
	v_fma_f32 v54, v54, v120, v70
	v_fma_f32 v55, v55, v120, v71
	v_fma_f32 v56, v56, v120, v72
	v_fma_f32 v57, v57, v120, v73
	v_fma_f32 v58, v58, v120, v74
	v_fma_f32 v59, v59, v120, v75
	v_fma_f32 v60, v60, v120, v76
	v_fma_f32 v61, v61, v120, v77
	v_fma_f32 v62, v62, v120, v78
	v_fma_f32 v63, v63, v120, v79
	ds_bpermute_b32 v64, v119, v32
	ds_bpermute_b32 v65, v119, v33
	ds_bpermute_b32 v66, v119, v34
	ds_bpermute_b32 v67, v119, v35
	ds_bpermute_b32 v68, v119, v36
	ds_bpermute_b32 v69, v119, v37
	ds_bpermute_b32 v70, v119, v38
	ds_bpermute_b32 v71, v119, v39
	ds_bpermute_b32 v72, v119, v40
	ds_bpermute_b32 v73, v119, v41
	ds_bpermute_b32 v74, v119, v42
	ds_bpermute_b32 v75, v119, v43
	ds_bpermute_b32 v76, v119, v44
	ds_bpermute_b32 v77, v119, v45
	ds_bpermute_b32 v78, v119, v46
	ds_bpermute_b32 v79, v119, v47
	s_waitcnt vmcnt(0) lgkmcnt(0)
	v_mul_f32_e32 v64, v121, v64
	v_mul_f32_e32 v65, v121, v65
	v_mul_f32_e32 v66, v121, v66
	v_mul_f32_e32 v67, v121, v67
	v_mul_f32_e32 v68, v121, v68
	v_mul_f32_e32 v69, v121, v69
	v_mul_f32_e32 v70, v121, v70
	v_mul_f32_e32 v71, v121, v71
	v_mul_f32_e32 v72, v121, v72
	v_mul_f32_e32 v73, v121, v73
	v_mul_f32_e32 v74, v121, v74
	v_mul_f32_e32 v75, v121, v75
	v_mul_f32_e32 v76, v121, v76
	v_mul_f32_e32 v77, v121, v77
	v_mul_f32_e32 v78, v121, v78
	v_mul_f32_e32 v79, v121, v79
	v_cndmask_b32_e64 v64, v64, -v64, s[100:101]
	v_cndmask_b32_e64 v65, v65, -v65, s[100:101]
	v_cndmask_b32_e64 v66, v66, -v66, s[100:101]
	v_cndmask_b32_e64 v67, v67, -v67, s[100:101]
	v_cndmask_b32_e64 v68, v68, -v68, s[100:101]
	v_cndmask_b32_e64 v69, v69, -v69, s[100:101]
	v_cndmask_b32_e64 v70, v70, -v70, s[100:101]
	v_cndmask_b32_e64 v71, v71, -v71, s[100:101]
	v_cndmask_b32_e64 v72, v72, -v72, s[100:101]
	v_cndmask_b32_e64 v73, v73, -v73, s[100:101]
	v_cndmask_b32_e64 v74, v74, -v74, s[100:101]
	v_cndmask_b32_e64 v75, v75, -v75, s[100:101]
	v_cndmask_b32_e64 v76, v76, -v76, s[100:101]
	v_cndmask_b32_e64 v77, v77, -v77, s[100:101]
	v_cndmask_b32_e64 v78, v78, -v78, s[100:101]
	v_cndmask_b32_e64 v79, v79, -v79, s[100:101]
	v_fma_f32 v32, v32, v120, v64
	v_fma_f32 v33, v33, v120, v65
	v_fma_f32 v34, v34, v120, v66
	v_fma_f32 v35, v35, v120, v67
	v_fma_f32 v36, v36, v120, v68
	v_fma_f32 v37, v37, v120, v69
	v_fma_f32 v38, v38, v120, v70
	v_fma_f32 v39, v39, v120, v71
	v_fma_f32 v40, v40, v120, v72
	v_fma_f32 v41, v41, v120, v73
	v_fma_f32 v42, v42, v120, v74
	v_fma_f32 v43, v43, v120, v75
	v_fma_f32 v44, v44, v120, v76
	v_fma_f32 v45, v45, v120, v77
	v_fma_f32 v46, v46, v120, v78
	v_fma_f32 v47, v47, v120, v79
	s_add_u32 s98, s90, 0x3464000
	s_addc_u32 s99, s91, 0
	global_load_dwordx2 v[80:81], v117, s[98:99]
	global_load_dwordx2 v[82:83], v117, s[98:99] offset:128
	global_load_dwordx2 v[84:85], v117, s[98:99] offset:256
	global_load_dwordx2 v[86:87], v117, s[98:99] offset:384
	global_load_dwordx2 v[88:89], v117, s[98:99] offset:1024
	global_load_dwordx2 v[90:91], v117, s[98:99] offset:1152
	global_load_dwordx2 v[92:93], v117, s[98:99] offset:1280
	global_load_dwordx2 v[94:95], v117, s[98:99] offset:1408
	global_load_dwordx2 v[96:97], v117, s[98:99] offset:2048
	global_load_dwordx2 v[98:99], v117, s[98:99] offset:2176
	global_load_dwordx2 v[100:101], v117, s[98:99] offset:2304
	global_load_dwordx2 v[102:103], v117, s[98:99] offset:2432
	global_load_dwordx2 v[104:105], v117, s[98:99] offset:3072
	global_load_dwordx2 v[106:107], v117, s[98:99] offset:3200
	global_load_dwordx2 v[108:109], v117, s[98:99] offset:3328
	global_load_dwordx2 v[110:111], v117, s[98:99] offset:3456
	ds_bpermute_b32 v64, v119, v16
	ds_bpermute_b32 v65, v119, v17
	ds_bpermute_b32 v66, v119, v18
	ds_bpermute_b32 v67, v119, v19
	ds_bpermute_b32 v68, v119, v20
	ds_bpermute_b32 v69, v119, v21
	ds_bpermute_b32 v70, v119, v22
	ds_bpermute_b32 v71, v119, v23
	ds_bpermute_b32 v72, v119, v24
	ds_bpermute_b32 v73, v119, v25
	ds_bpermute_b32 v74, v119, v26
	ds_bpermute_b32 v75, v119, v27
	ds_bpermute_b32 v76, v119, v28
	ds_bpermute_b32 v77, v119, v29
	ds_bpermute_b32 v78, v119, v30
	ds_bpermute_b32 v79, v119, v31
	s_waitcnt vmcnt(0) lgkmcnt(0)
	v_mul_f32_e32 v64, v81, v64
	v_mul_f32_e32 v65, v83, v65
	v_mul_f32_e32 v66, v85, v66
	v_mul_f32_e32 v67, v87, v67
	v_mul_f32_e32 v68, v89, v68
	v_mul_f32_e32 v69, v91, v69
	v_mul_f32_e32 v70, v93, v70
	v_mul_f32_e32 v71, v95, v71
	v_mul_f32_e32 v72, v97, v72
	v_mul_f32_e32 v73, v99, v73
	v_mul_f32_e32 v74, v101, v74
	v_mul_f32_e32 v75, v103, v75
	v_mul_f32_e32 v76, v105, v76
	v_mul_f32_e32 v77, v107, v77
	v_mul_f32_e32 v78, v109, v78
	v_mul_f32_e32 v79, v111, v79
	v_cndmask_b32_e64 v64, v64, -v64, s[100:101]
	v_cndmask_b32_e64 v65, v65, -v65, s[100:101]
	v_cndmask_b32_e64 v66, v66, -v66, s[100:101]
	v_cndmask_b32_e64 v67, v67, -v67, s[100:101]
	v_cndmask_b32_e64 v68, v68, -v68, s[100:101]
	v_cndmask_b32_e64 v69, v69, -v69, s[100:101]
	v_cndmask_b32_e64 v70, v70, -v70, s[100:101]
	v_cndmask_b32_e64 v71, v71, -v71, s[100:101]
	v_cndmask_b32_e64 v72, v72, -v72, s[100:101]
	v_cndmask_b32_e64 v73, v73, -v73, s[100:101]
	v_cndmask_b32_e64 v74, v74, -v74, s[100:101]
	v_cndmask_b32_e64 v75, v75, -v75, s[100:101]
	v_cndmask_b32_e64 v76, v76, -v76, s[100:101]
	v_cndmask_b32_e64 v77, v77, -v77, s[100:101]
	v_cndmask_b32_e64 v78, v78, -v78, s[100:101]
	v_cndmask_b32_e64 v79, v79, -v79, s[100:101]
	v_fma_f32 v16, v16, v80, v64
	v_fma_f32 v17, v17, v82, v65
	v_fma_f32 v18, v18, v84, v66
	v_fma_f32 v19, v19, v86, v67
	v_fma_f32 v20, v20, v88, v68
	v_fma_f32 v21, v21, v90, v69
	v_fma_f32 v22, v22, v92, v70
	v_fma_f32 v23, v23, v94, v71
	v_fma_f32 v24, v24, v96, v72
	v_fma_f32 v25, v25, v98, v73
	v_fma_f32 v26, v26, v100, v74
	v_fma_f32 v27, v27, v102, v75
	v_fma_f32 v28, v28, v104, v76
	v_fma_f32 v29, v29, v106, v77
	v_fma_f32 v30, v30, v108, v78
	v_fma_f32 v31, v31, v110, v79
	s_add_u32 s98, s90, 0x3465000
	s_addc_u32 s99, s91, 0
	global_load_dwordx2 v[80:81], v117, s[98:99]
	global_load_dwordx2 v[82:83], v117, s[98:99] offset:128
	global_load_dwordx2 v[84:85], v117, s[98:99] offset:256
	global_load_dwordx2 v[86:87], v117, s[98:99] offset:384
	global_load_dwordx2 v[88:89], v117, s[98:99] offset:1024
	global_load_dwordx2 v[90:91], v117, s[98:99] offset:1152
	global_load_dwordx2 v[92:93], v117, s[98:99] offset:1280
	global_load_dwordx2 v[94:95], v117, s[98:99] offset:1408
	global_load_dwordx2 v[96:97], v117, s[98:99] offset:2048
	global_load_dwordx2 v[98:99], v117, s[98:99] offset:2176
	global_load_dwordx2 v[100:101], v117, s[98:99] offset:2304
	global_load_dwordx2 v[102:103], v117, s[98:99] offset:2432
	global_load_dwordx2 v[104:105], v117, s[98:99] offset:3072
	global_load_dwordx2 v[106:107], v117, s[98:99] offset:3200
	global_load_dwordx2 v[108:109], v117, s[98:99] offset:3328
	global_load_dwordx2 v[110:111], v117, s[98:99] offset:3456
	ds_bpermute_b32 v64, v119, v0
	ds_bpermute_b32 v65, v119, v1
	ds_bpermute_b32 v66, v119, v2
	ds_bpermute_b32 v67, v119, v3
	ds_bpermute_b32 v68, v119, v4
	ds_bpermute_b32 v69, v119, v5
	ds_bpermute_b32 v70, v119, v6
	ds_bpermute_b32 v71, v119, v7
	ds_bpermute_b32 v72, v119, v8
	ds_bpermute_b32 v73, v119, v9
	ds_bpermute_b32 v74, v119, v10
	ds_bpermute_b32 v75, v119, v11
	ds_bpermute_b32 v76, v119, v12
	ds_bpermute_b32 v77, v119, v13
	ds_bpermute_b32 v78, v119, v14
	ds_bpermute_b32 v79, v119, v15
	s_waitcnt vmcnt(0) lgkmcnt(0)
	v_mul_f32_e32 v64, v81, v64
	v_mul_f32_e32 v65, v83, v65
	v_mul_f32_e32 v66, v85, v66
	v_mul_f32_e32 v67, v87, v67
	v_mul_f32_e32 v68, v89, v68
	v_mul_f32_e32 v69, v91, v69
	v_mul_f32_e32 v70, v93, v70
	v_mul_f32_e32 v71, v95, v71
	v_mul_f32_e32 v72, v97, v72
	v_mul_f32_e32 v73, v99, v73
	v_mul_f32_e32 v74, v101, v74
	v_mul_f32_e32 v75, v103, v75
	v_mul_f32_e32 v76, v105, v76
	v_mul_f32_e32 v77, v107, v77
	v_mul_f32_e32 v78, v109, v78
	v_mul_f32_e32 v79, v111, v79
	v_cndmask_b32_e64 v64, v64, -v64, s[100:101]
	v_cndmask_b32_e64 v65, v65, -v65, s[100:101]
	v_cndmask_b32_e64 v66, v66, -v66, s[100:101]
	v_cndmask_b32_e64 v67, v67, -v67, s[100:101]
	v_cndmask_b32_e64 v68, v68, -v68, s[100:101]
	v_cndmask_b32_e64 v69, v69, -v69, s[100:101]
	v_cndmask_b32_e64 v70, v70, -v70, s[100:101]
	v_cndmask_b32_e64 v71, v71, -v71, s[100:101]
	v_cndmask_b32_e64 v72, v72, -v72, s[100:101]
	v_cndmask_b32_e64 v73, v73, -v73, s[100:101]
	v_cndmask_b32_e64 v74, v74, -v74, s[100:101]
	v_cndmask_b32_e64 v75, v75, -v75, s[100:101]
	v_cndmask_b32_e64 v76, v76, -v76, s[100:101]
	v_cndmask_b32_e64 v77, v77, -v77, s[100:101]
	v_cndmask_b32_e64 v78, v78, -v78, s[100:101]
	v_cndmask_b32_e64 v79, v79, -v79, s[100:101]
	v_fma_f32 v0, v0, v80, v64
	v_fma_f32 v1, v1, v82, v65
	v_fma_f32 v2, v2, v84, v66
	v_fma_f32 v3, v3, v86, v67
	v_fma_f32 v4, v4, v88, v68
	v_fma_f32 v5, v5, v90, v69
	v_fma_f32 v6, v6, v92, v70
	v_fma_f32 v7, v7, v94, v71
	v_fma_f32 v8, v8, v96, v72
	v_fma_f32 v9, v9, v98, v73
	v_fma_f32 v10, v10, v100, v74
	v_fma_f32 v11, v11, v102, v75
	v_fma_f32 v12, v12, v104, v76
	v_fma_f32 v13, v13, v106, v77
	v_fma_f32 v14, v14, v108, v78
	v_fma_f32 v15, v15, v110, v79
	s_branch .Lodin4_norope
